# P3: next K/V tile global loads issued before the end-of-step barrier (right after the staging registers are written to LDS) instead of at the next loop head
# baseline (speedup 1.0000x reference)
; template <int MODE>
; __device__ void attn_item(const Params& p, char* lds, int grp  , int b, int h, int qblk, int dry) {
;     ...
;   u32x4 rk[NKC], rv[NVC];
;   int koff[NKC], voff[NVC];
; #pragma unroll
;   for (int i = 0; i < NKC; ++i) { const int q = tid + 256 * i; koff[i] = (q / KCH) * LDH + (q % KCH) * 8; }
; #pragma unroll
;   for (int i = 0; i < NVC; ++i) { const int q = tid + 256 * i; voff[i] = (q >> 3) * Lk + (q & 7) * 8; }
;   auto gloadK = [&](int kt) {
;     const bf16_t* ktile = kg + (size_t)kt * 64 * LDH;
; #pragma unroll
;     for (int i = 0; i < NKC; ++i) {
;       if (MODE == 0) rk[i] = *(const u32x4*)(ktile + koff[i]);
;       else {
;         const int q = tid + 256 * i; const int row = q / KCH, ch = q % KCH;
;         const bf16_t* src = (ch < 8) ? kg + (size_t)(kt * 64 + row) * LDH + ch * 8 : kpe + (size_t)(kt * 64 + row) * 32 + (ch - 8) * 8;
;         rk[i] = *(const u32x4*)src;
;       }
;     }
;   };
;   auto gloadV = [&](int kt) {
;     const bf16_t* vtile = vg + kt * 64;
; #pragma unroll
;     for (int i = 0; i < NVC; ++i) rv[i] = *(const u32x4*)(vtile + voff[i]);
;   };
;   auto lwriteK = [&](int buf) {
;     char* base = lds + buf * BUF;
; #pragma unroll
;     for (int i = 0; i < NKC; ++i) { const int q = tid + 256 * i; const int row = q / KCH, ch = q % KCH; *(u32x4*)(base + row * KSTR + ch * 16) = rk[i]; }
;   };
;   auto lwriteV = [&](int buf) {
;     char* base = lds + buf * BUF;
; #pragma unroll
;     for (int i = 0; i < NVC; ++i) { const int q = tid + 256 * i; const int row = q >> 3, ch = q & 7; *(u32x4*)(base + KBYTES + row * 144 + ch * 16) = rv[i]; }
;   };
;   f32x16 O[DV / 32];
; #pragma unroll
;   for (int i = 0; i < DV / 32; ++i)
; #pragma unroll
;     for (int r = 0; r < 16; ++r) O[i][r] = 0.f;
;   float m = -1e30f, l = 0.f;
;   const float* btab = (const float*)(ws + W_MISC) + 64 + h * 192;
;   __shared__ float s_bt[192];
;   if (MODE == 0 && tid < 192) s_bt[tid] = btab[tid];
;   gloadK(0); gloadV(0); lwriteK(0); lwriteV(0);
;   __syncthreads();
.LBB0_447:
	s_or_b64 exec, exec, s[26:27]
	s_lshl_b32 s50, s52, 7
	s_and_b64 s[26:27], s[0:1], exec
	s_movk_i32 s26, 0x1040
	s_cselect_b32 s27, s26, 0x840
	s_add_i32 s26, s45, 1
	s_and_b64 s[0:1], s[0:1], exec
	s_mul_i32 s52, s49, 0x880
	s_cselect_b32 s26, s26, 33
	s_mul_hi_u32 s45, s49, 0x880
	s_add_u32 s0, s33, s52
	s_addc_u32 s1, s28, s45
	s_lshl_b32 s49, s50, 1
	s_add_u32 s0, s0, s49
	s_addc_u32 s1, s1, 0
	s_lshl_b32 s48, s48, 10
	s_or_b32 s48, s50, s48
	s_add_u32 s49, s96, s2
	v_mul_u32_u24_e32 v0, s27, v233
	s_addc_u32 s50, s97, s3
	s_mul_i32 s2, s51, s48
	s_mov_b32 s3, s25
	v_or_b32_e32 v16, v0, v169
	v_mul_u32_u24_e32 v0, s27, v170
	s_lshl_b64 s[2:3], s[2:3], 1
	v_or_b32_e32 v18, v0, v169
	v_mul_u32_u24_e32 v0, s27, v171
	s_add_u32 s48, s49, s2
	v_or_b32_e32 v20, v0, v169
	v_mul_u32_u24_e32 v0, s27, v172
	s_addc_u32 s49, s50, s3
	v_or_b32_e32 v22, v0, v169
	v_lshlrev_b32_e32 v0, 1, v16
	global_load_dwordx4 v[112:115], v197, s[0:1]
	global_load_dwordx4 v[116:119], v198, s[0:1]
	global_load_dwordx4 v[120:123], v199, s[0:1]
	global_load_dwordx4 v[124:127], v200, s[0:1]
	v_lshlrev_b32_e32 v1, 1, v18
	global_load_dwordx4 v[128:131], v0, s[48:49]
	global_load_dwordx4 v[132:135], v1, s[48:49]
	v_lshlrev_b32_e32 v0, 1, v20
	v_lshlrev_b32_e32 v1, 1, v22
	global_load_dwordx4 v[136:139], v0, s[48:49]
	global_load_dwordx4 v[140:143], v1, s[48:49]
	s_add_i32 s2, s44, 0xffffffa5
	s_add_u32 s0, s52, s24
	v_add_u32_e32 v0, s44, v147
	v_mov_b32_e32 v32, v145
	v_mov_b32_e32 v33, v145
	v_mov_b32_e32 v46, v145
	v_mov_b32_e32 v47, v145
	s_addc_u32 s1, s45, 0
	v_mov_b32_e32 v34, v145
	v_mov_b32_e32 v35, v145
	v_mov_b32_e32 v36, v145
	v_mov_b32_e32 v37, v145
	v_mov_b32_e32 v38, v145
	v_mov_b32_e32 v39, v145
	v_mov_b32_e32 v40, v145
	v_mov_b32_e32 v41, v145
	v_mov_b32_e32 v42, v145
	v_mov_b32_e32 v43, v145
	v_mov_b32_e32 v44, v145
	v_mov_b32_e32 v45, v145
	v_sub_u32_e32 v165, v146, v0
	v_mov_b64_e32 v[62:63], v[46:47]
	v_mov_b64_e32 v[0:1], v[32:33]
	v_lshlrev_b32_e32 v212, 1, v16
	v_lshlrev_b32_e32 v213, 1, v18
	v_lshlrev_b32_e32 v214, 1, v20
	v_lshlrev_b32_e32 v215, 1, v22
	s_add_u32 s50, s96, s0
	v_mov_b64_e32 v[16:17], v[32:33]
	s_mov_b32 s27, 0
	v_mov_b32_e32 v168, 0xf149f2ca
	v_mov_b32_e32 v161, 0
	v_mov_b64_e32 v[60:61], v[44:45]
	v_mov_b64_e32 v[58:59], v[42:43]
	v_mov_b64_e32 v[56:57], v[40:41]
	v_mov_b64_e32 v[54:55], v[38:39]
	v_mov_b64_e32 v[52:53], v[36:37]
	v_mov_b64_e32 v[50:51], v[34:35]
	v_mov_b64_e32 v[48:49], v[32:33]
	v_mov_b64_e32 v[2:3], v[34:35]
	v_mov_b64_e32 v[4:5], v[36:37]
	v_mov_b64_e32 v[6:7], v[38:39]
	v_mov_b64_e32 v[8:9], v[40:41]
	v_mov_b64_e32 v[10:11], v[42:43]
	v_mov_b64_e32 v[12:13], v[44:45]
	v_mov_b64_e32 v[14:15], v[46:47]
	s_mov_b32 s24, 64
	s_addc_u32 s51, s97, s1
	v_mov_b64_e32 v[18:19], v[34:35]
	v_mov_b64_e32 v[20:21], v[36:37]
	v_mov_b64_e32 v[22:23], v[38:39]
	v_mov_b64_e32 v[24:25], v[40:41]
	v_mov_b64_e32 v[26:27], v[42:43]
	v_mov_b64_e32 v[28:29], v[44:45]
	v_mov_b64_e32 v[30:31], v[46:47]
	s_waitcnt vmcnt(7)
	ds_write_b128 v201, v[112:115]
	s_waitcnt vmcnt(6)
	ds_write_b128 v202, v[116:119]
	s_waitcnt vmcnt(5)
	ds_write_b128 v203, v[120:123]
	s_waitcnt vmcnt(4)
	ds_write_b128 v204, v[124:127]
	s_waitcnt vmcnt(3)
	ds_write_b128 v205, v[128:131] offset:17408
	s_waitcnt vmcnt(2)
	ds_write_b128 v206, v[132:135] offset:17408
	s_waitcnt vmcnt(1)
	ds_write_b128 v207, v[136:139] offset:17408
	s_waitcnt vmcnt(0)
	ds_write_b128 v208, v[140:143] offset:17408
	s_cmp_gt_u32 s26, 1
	s_cbranch_scc0 .Lp3_nold0
	v_lshl_add_u64 v[216:217], s[50:51], 0, v[152:153]
	v_lshl_add_u64 v[218:219], s[50:51], 0, v[154:155]
	global_load_dwordx4 v[112:115], v[216:217], off
	global_load_dwordx4 v[116:119], v[218:219], off
	v_lshl_add_u64 v[216:217], s[50:51], 0, v[156:157]
	v_lshl_add_u64 v[218:219], s[50:51], 0, v[158:159]
	global_load_dwordx4 v[120:123], v[216:217], off
	global_load_dwordx4 v[124:127], v[218:219], off
	s_lshl_b64 s[44:45], s[24:25], 1
	s_add_u32 s44, s48, s44
	s_addc_u32 s45, s49, s45
	global_load_dwordx4 v[128:131], v212, s[44:45]
	global_load_dwordx4 v[132:135], v213, s[44:45]
	global_load_dwordx4 v[136:139], v214, s[44:45]
	global_load_dwordx4 v[140:143], v215, s[44:45]
.Lp3_nold0:
	s_waitcnt lgkmcnt(0)
	s_barrier
; __device__ __forceinline__ f32x16 mfma32(bf16x8 a, bf16x8 b, f32x16 c) { return __builtin_amdgcn_mfma_f32_32x32x16_bf16(a, b, c, 0, 0, 0); }
; __device__ __forceinline__ int accrow(int reg, int hh) { return (reg & 3) + 8 * (reg >> 2) + 4 * hh; }
; template <int MODE>
; __device__ void attn_item(const Params& p, char* lds, int grp  , int b, int h, int qblk, int dry) {
;     ...
;   for (int kt = 0; kt < nkt; ++kt) {
;     const bool more = (kt + 1 < nkt);
;     if (more) { gloadK(kt + 1); if (MODE == 1) gloadV(kt + 1); }
;     if (active && kt <= my_last) {
;       const char* base = lds + (kt & 1) * BUF;
;       f32x16 S[2];
;       const char* kp0 = base + l31 * KSTR + comp * 128 + hh * 16;
;       {
;         bf16x8 kf0[DQ / 16], kf1[DQ / 16];
; #pragma unroll
;         for (int ks = 0; ks < DQ / 16; ++ks) kf0[ks] = *(const bf16x8*)(kp0 + ks * 32);
;         __builtin_amdgcn_sched_barrier(0);
; #pragma unroll
;         for (int ks = 0; ks < DQ / 16; ++ks) kf1[ks] = *(const bf16x8*)(kp0 + 32 * KSTR + ks * 32);
; #pragma unroll
;         for (int r = 0; r < 16; ++r) { S[0][r] = 0.f; S[1][r] = 0.f; }
; #pragma unroll
;         for (int ks = 0; ks < DQ / 16; ++ks) S[0] = mfma32(kf0[ks], qf[ks], S[0]);
; #pragma unroll
;         for (int ks = 0; ks < DQ / 16; ++ks) S[1] = mfma32(kf1[ks], qf[ks], S[1]);
;       }
;       if (MODE == 0) {
;         const int kpos0 = kt * 64;
;         if (kpos0 + 63 > qpos0 - 91) {
; #pragma unroll
;           for (int sub = 0; sub < 2; ++sub)
; #pragma unroll
;             for (int r = 0; r < 16; ++r) {
;               int rel = kpos0 + sub * 32 + accrow(r, hh) - qpos; rel = rel < -128 ? -128 : rel;
;               S[sub][r] += s_bt[rel + 128];
;             }
;         }
.LBB0_448:
	s_add_i32 s3, s27, 1
	s_cmp_lt_u32 s3, s26
	s_cselect_b64 s[0:1], -1, 0
	s_bitcmp1_b32 s27, 0
	s_cselect_b32 s27, 0x8c00, 0
	v_add_u32_e32 v64, s27, v193
	v_add3_u32 v220, v64, v194, v182
	ds_read_b128 v[64:67], v220
	ds_read_b128 v[68:71], v220 offset:32
	ds_read_b128 v[72:75], v220 offset:64
	ds_read_b128 v[76:79], v220 offset:96
	s_waitcnt lgkmcnt(3)
	v_mfma_f32_32x32x16_bf16 v[80:95], v[64:67], v[96:99], 0
	ds_read_b128 v[64:67], v220 offset:8704
	ds_read_b128 v[216:219], v220 offset:8736
	ds_read_b128 v[238:241], v220 offset:8768
	ds_read_b128 v[242:245], v220 offset:8800
	s_add_i32 s44, s24, -1
	s_cmp_le_i32 s44, s2
	s_waitcnt lgkmcnt(6)
	v_mfma_f32_32x32x16_bf16 v[80:95], v[68:71], v[100:103], v[80:95]
	s_waitcnt lgkmcnt(5)
	v_mfma_f32_32x32x16_bf16 v[80:95], v[72:75], v[104:107], v[80:95]
	s_waitcnt lgkmcnt(4)
	v_mfma_f32_32x32x16_bf16 v[80:95], v[76:79], v[108:111], v[80:95]
	s_waitcnt lgkmcnt(3)
	v_mfma_f32_32x32x16_bf16 v[64:79], v[64:67], v[96:99], 0
	s_waitcnt lgkmcnt(2)
	v_mfma_f32_32x32x16_bf16 v[64:79], v[216:219], v[100:103], v[64:79]
	s_waitcnt lgkmcnt(1)
	v_mfma_f32_32x32x16_bf16 v[64:79], v[238:241], v[104:107], v[64:79]
	s_waitcnt lgkmcnt(0)
	v_mfma_f32_32x32x16_bf16 v[64:79], v[242:245], v[108:111], v[64:79]
	s_cbranch_scc1 .LBB0_452
	v_add_u32_e32 v220, s24, v165
	v_subrev_u32_e32 v216, 64, v220
	v_max_i32_e32 v216, 0xffffff80, v216
	v_lshl_add_u32 v238, v216, 2, v210
	v_subrev_u32_e32 v216, 63, v220
	v_max_i32_e32 v216, 0xffffff80, v216
	v_lshl_add_u32 v239, v216, 2, v210
	v_subrev_u32_e32 v216, 62, v220
	v_max_i32_e32 v216, 0xffffff80, v216
	v_lshl_add_u32 v240, v216, 2, v210
	v_subrev_u32_e32 v216, 61, v220
	v_max_i32_e32 v216, 0xffffff80, v216
	v_lshl_add_u32 v241, v216, 2, v210
	v_subrev_u32_e32 v216, 56, v220
	v_max_i32_e32 v216, 0xffffff80, v216
	v_lshl_add_u32 v242, v216, 2, v210
	v_subrev_u32_e32 v216, 55, v220
	v_max_i32_e32 v216, 0xffffff80, v216
	v_lshl_add_u32 v243, v216, 2, v210
	v_subrev_u32_e32 v216, 54, v220
	v_max_i32_e32 v216, 0xffffff80, v216
	v_lshl_add_u32 v244, v216, 2, v210
	v_subrev_u32_e32 v216, 53, v220
	v_max_i32_e32 v216, 0xffffff80, v216
	v_lshl_add_u32 v245, v216, 2, v210
	v_subrev_u32_e32 v216, 48, v220
	v_subrev_u32_e32 v217, 47, v220
	v_subrev_u32_e32 v218, 46, v220
	v_subrev_u32_e32 v219, 45, v220
	v_subrev_u32_e32 v234, 40, v220
	v_subrev_u32_e32 v235, 39, v220
	v_subrev_u32_e32 v236, 38, v220
	v_subrev_u32_e32 v237, 37, v220
	v_max_i32_e32 v216, 0xffffff80, v216
	v_max_i32_e32 v217, 0xffffff80, v217
	v_max_i32_e32 v218, 0xffffff80, v218
	v_max_i32_e32 v219, 0xffffff80, v219
	v_max_i32_e32 v234, 0xffffff80, v234
	v_max_i32_e32 v235, 0xffffff80, v235
	v_max_i32_e32 v236, 0xffffff80, v236
	v_max_i32_e32 v237, 0xffffff80, v237
	v_lshl_add_u32 v216, v216, 2, v210
	v_lshl_add_u32 v217, v217, 2, v210
	v_lshl_add_u32 v218, v218, 2, v210
	v_lshl_add_u32 v219, v219, 2, v210
	v_lshl_add_u32 v234, v234, 2, v210
	v_lshl_add_u32 v235, v235, 2, v210
	v_lshl_add_u32 v236, v236, 2, v210
	v_lshl_add_u32 v237, v237, 2, v210
	ds_read_b32 v216, v216
	ds_read_b32 v217, v217
	ds_read_b32 v218, v218
	ds_read_b32 v219, v219
	ds_read_b32 v234, v234
	ds_read_b32 v235, v235
	ds_read_b32 v236, v236
	ds_read_b32 v237, v237
	ds_read_b32 v238, v238
	ds_read_b32 v239, v239
	ds_read_b32 v240, v240
	ds_read_b32 v241, v241
	ds_read_b32 v242, v242
	ds_read_b32 v243, v243
	ds_read_b32 v244, v244
	ds_read_b32 v245, v245
	s_waitcnt lgkmcnt(14)
	v_add_f32_e32 v88, v88, v216
	v_add_f32_e32 v89, v89, v217
	v_subrev_u32_e32 v216, 32, v220
	v_max_i32_e32 v216, 0xffffff80, v216
	s_waitcnt lgkmcnt(6)
	v_add_f32_e32 v80, v80, v238
	v_add_f32_e32 v81, v81, v239
	v_lshl_add_u32 v238, v216, 2, v210
	v_subrev_u32_e32 v216, 31, v220
	v_max_i32_e32 v216, 0xffffff80, v216
	v_lshl_add_u32 v239, v216, 2, v210
	v_subrev_u32_e32 v216, 30, v220
	v_max_i32_e32 v216, 0xffffff80, v216
	s_waitcnt lgkmcnt(4)
	v_add_f32_e32 v82, v82, v240
	v_add_f32_e32 v83, v83, v241
	v_lshl_add_u32 v240, v216, 2, v210
	v_subrev_u32_e32 v216, 29, v220
	v_max_i32_e32 v216, 0xffffff80, v216
	v_lshl_add_u32 v241, v216, 2, v210
	v_subrev_u32_e32 v216, 24, v220
	v_max_i32_e32 v216, 0xffffff80, v216
	s_waitcnt lgkmcnt(2)
	v_add_f32_e32 v84, v84, v242
	v_add_f32_e32 v85, v85, v243
	v_lshl_add_u32 v242, v216, 2, v210
	v_subrev_u32_e32 v216, 23, v220
	v_max_i32_e32 v216, 0xffffff80, v216
	v_lshl_add_u32 v243, v216, 2, v210
	v_subrev_u32_e32 v216, 22, v220
	v_max_i32_e32 v216, 0xffffff80, v216
	s_waitcnt lgkmcnt(0)
	v_add_f32_e32 v86, v86, v244
	v_add_f32_e32 v87, v87, v245
	v_lshl_add_u32 v244, v216, 2, v210
	v_subrev_u32_e32 v216, 21, v220
	v_max_i32_e32 v216, 0xffffff80, v216
	v_add_f32_e32 v94, v94, v236
	v_add_f32_e32 v95, v95, v237
	v_add_f32_e32 v92, v92, v234
	v_add_f32_e32 v93, v93, v235
	v_add_f32_e32 v90, v90, v218
	v_add_f32_e32 v91, v91, v219
	v_lshl_add_u32 v245, v216, 2, v210
	v_add_u32_e32 v216, -16, v220
	v_add_u32_e32 v217, -15, v220
	v_add_u32_e32 v218, -14, v220
	v_add_u32_e32 v219, -13, v220
	v_add_u32_e32 v234, -8, v220
	v_add_u32_e32 v235, -7, v220
	v_add_u32_e32 v236, -6, v220
	v_max_i32_e32 v216, 0xffffff80, v216
	v_max_i32_e32 v217, 0xffffff80, v217
	v_max_i32_e32 v218, 0xffffff80, v218
	v_max_i32_e32 v219, 0xffffff80, v219
	v_max_i32_e32 v234, 0xffffff80, v234
	v_max_i32_e32 v235, 0xffffff80, v235
	v_max_i32_e32 v236, 0xffffff80, v236
	v_add_u32_e32 v220, -5, v220
	v_lshl_add_u32 v216, v216, 2, v210
	v_lshl_add_u32 v217, v217, 2, v210
	v_lshl_add_u32 v218, v218, 2, v210
	v_lshl_add_u32 v219, v219, 2, v210
	v_lshl_add_u32 v234, v234, 2, v210
	v_lshl_add_u32 v235, v235, 2, v210
	v_lshl_add_u32 v236, v236, 2, v210
	v_max_i32_e32 v220, 0xffffff80, v220
	v_lshl_add_u32 v220, v220, 2, v210
	ds_read_b32 v216, v216
	ds_read_b32 v217, v217
	ds_read_b32 v218, v218
	ds_read_b32 v219, v219
	ds_read_b32 v234, v234
	ds_read_b32 v235, v235
	ds_read_b32 v236, v236
	ds_read_b32 v237, v220
	ds_read_b32 v238, v238
	ds_read_b32 v239, v239
	ds_read_b32 v240, v240
	ds_read_b32 v241, v241
	ds_read_b32 v242, v242
	ds_read_b32 v243, v243
	ds_read_b32 v244, v244
	ds_read_b32 v245, v245
	s_waitcnt lgkmcnt(8)
	v_add_f32_e32 v78, v78, v236
	v_add_f32_e32 v79, v79, v237
	v_add_f32_e32 v76, v76, v234
	v_add_f32_e32 v77, v77, v235
	v_add_f32_e32 v74, v74, v218
	v_add_f32_e32 v75, v75, v219
	v_add_f32_e32 v72, v72, v216
	v_add_f32_e32 v73, v73, v217
	s_waitcnt lgkmcnt(0)
	v_add_f32_e32 v70, v70, v244
	v_add_f32_e32 v71, v71, v245
	v_add_f32_e32 v68, v68, v242
	v_add_f32_e32 v69, v69, v243
	v_add_f32_e32 v66, v66, v240
	v_add_f32_e32 v67, v67, v241
	v_add_f32_e32 v64, v64, v238
	v_add_f32_e32 v65, v65, v239

; template <int MODE>
; __device__ void attn_item(const Params& p, char* lds, int grp  , int b, int h, int qblk, int dry) {
;     ...
;   auto gloadK = [&](int kt) {
;     const bf16_t* ktile = kg + (size_t)kt * 64 * LDH;
; #pragma unroll
;     for (int i = 0; i < NKC; ++i) {
;       if (MODE == 0) rk[i] = *(const u32x4*)(ktile + koff[i]);
;       else {
;         const int q = tid + 256 * i; const int row = q / KCH, ch = q % KCH;
;         const bf16_t* src = (ch < 8) ? kg + (size_t)(kt * 64 + row) * LDH + ch * 8 : kpe + (size_t)(kt * 64 + row) * 32 + (ch - 8) * 8;
;         rk[i] = *(const u32x4*)src;
;       }
;     }
;   };
;   auto gloadV = [&](int kt) {
;     const bf16_t* vtile = vg + kt * 64;
; #pragma unroll
;     for (int i = 0; i < NVC; ++i) rv[i] = *(const u32x4*)(vtile + voff[i]);
;   };
;     ...
;       l += ps2[0] + ps2[1];
;     }
;     if (more) { if (MODE == 1) lwriteK((kt + 1) & 1); lwriteV((kt + 1) & 1); }
;     __syncthreads();
;   }
.LBB0_458:
	v_add_f32_e32 v80, 0, v80
	v_add_f32_e32 v81, 0, v81
	s_add_i32 s24, s24, 64
	v_add_f32_e32 v80, v82, v80
	v_add_f32_e32 v81, v83, v81
	s_add_u32 s50, s50, 0x22000
	v_add_f32_e32 v80, v84, v80
	v_add_f32_e32 v81, v85, v81
	s_addc_u32 s51, s51, 0
	v_add_f32_e32 v80, v86, v80
	v_add_f32_e32 v81, v87, v81
	s_add_i32 s44, s3, 1
	s_cmp_lt_u32 s44, s26
	s_cbranch_scc0 .Lp3_nold
	v_lshl_add_u64 v[216:217], s[50:51], 0, v[152:153]
	v_lshl_add_u64 v[218:219], s[50:51], 0, v[154:155]
	global_load_dwordx4 v[112:115], v[216:217], off
	global_load_dwordx4 v[116:119], v[218:219], off
	v_lshl_add_u64 v[216:217], s[50:51], 0, v[156:157]
	v_lshl_add_u64 v[218:219], s[50:51], 0, v[158:159]
	global_load_dwordx4 v[120:123], v[216:217], off
	global_load_dwordx4 v[124:127], v[218:219], off
	s_lshl_b64 s[44:45], s[24:25], 1
	s_add_u32 s44, s48, s44
	s_addc_u32 s45, s49, s45
	global_load_dwordx4 v[128:131], v212, s[44:45]
	global_load_dwordx4 v[132:135], v213, s[44:45]
	global_load_dwordx4 v[136:139], v214, s[44:45]
	global_load_dwordx4 v[140:143], v215, s[44:45]
.Lp3_nold:
	s_cmp_eq_u32 s26, s3
	v_add_f32_e32 v80, v88, v80
	v_add_f32_e32 v81, v89, v81
	s_waitcnt lgkmcnt(0)
	v_add_f32_e32 v80, v90, v80
	v_add_f32_e32 v81, v91, v81
	s_barrier
	v_add_f32_e32 v80, v92, v80
	v_add_f32_e32 v81, v93, v81
	v_add_f32_e32 v80, v94, v80
	v_add_f32_e32 v81, v95, v81
	v_add_f32_e32 v64, v64, v80
	v_add_f32_e32 v65, v65, v81
	v_add_f32_e32 v64, v66, v64
	v_add_f32_e32 v65, v67, v65
	v_add_f32_e32 v64, v68, v64
	v_add_f32_e32 v65, v69, v65
	v_add_f32_e32 v64, v70, v64
	v_add_f32_e32 v65, v71, v65
	v_add_f32_e32 v64, v72, v64
	v_add_f32_e32 v65, v73, v65
	v_add_f32_e32 v64, v74, v64
	v_add_f32_e32 v65, v75, v65
	v_add_f32_e32 v64, v76, v64
	v_add_f32_e32 v65, v77, v65
	v_add_f32_e32 v64, v78, v64
	v_add_f32_e32 v65, v79, v65
	v_add_f32_e32 v64, v64, v65
	v_add_f32_e32 v161, v161, v64
	s_cbranch_scc1 .LBB0_460
	s_mov_b32 s27, s3
	s_branch .LBB0_448
